# v36 + prologue weight-conversion loop waits count all 32 stores issued after the prefetched loads (was 8): no per-tile store drain
# baseline (speedup 1.0000x reference)
.LBB0_110:
	s_lshl_b32 s57, s4, 1
	s_lshl_b32 s58, s5, 1
	v_or_b32_e32 v5, s57, v1
	v_or_b32_e32 v12, s58, v138
	s_add_i32 s60, s57, 4
	s_add_i32 s61, s58, 4
	s_add_i32 s62, s57, 8
	s_add_i32 s63, s58, 8
	s_add_i32 s57, s57, 12
	s_add_i32 s64, s58, 12
	v_mad_u64_u32 v[8:9], s[58:59], v12, s3, v[140:141]
	v_mad_u64_u32 v[10:11], s[58:59], v5, s3, v[140:141]
	v_add_u32_e32 v5, v5, v3
	v_add_u32_e32 v24, v12, v132
	v_or_b32_e32 v16, s60, v1
	v_or_b32_e32 v17, s61, v138
	v_or_b32_e32 v20, s62, v1
	v_or_b32_e32 v21, s63, v138
	v_or_b32_e32 v25, s57, v1
	v_or_b32_e32 v26, s64, v138
	ds_read2_b32 v[8:9], v8 offset1:1
	ds_read2_b32 v[10:11], v10 offset1:1
	v_mul_hi_i32 v27, v24, s92
	v_mul_hi_i32 v28, v5, s92
	v_mad_u64_u32 v[12:13], s[58:59], v17, s3, v[140:141]
	v_mad_u64_u32 v[14:15], s[58:59], v16, s3, v[140:141]
	v_add_u32_e32 v29, v16, v3
	v_add_u32_e32 v30, v17, v132
	v_mad_u64_u32 v[16:17], s[58:59], v21, s3, v[140:141]
	v_mad_u64_u32 v[18:19], s[58:59], v20, s3, v[140:141]
	v_add_u32_e32 v31, v20, v3
	v_add_u32_e32 v32, v21, v132
	v_mad_u64_u32 v[20:21], s[58:59], v26, s3, v[140:141]
	v_mad_u64_u32 v[22:23], s[58:59], v25, s3, v[140:141]
	v_add_u32_e32 v25, v25, v3
	v_add_u32_e32 v26, v26, v132
	v_lshrrev_b32_e32 v33, 31, v27
	v_ashrrev_i32_e32 v27, 9, v27
	v_lshrrev_b32_e32 v34, 31, v28
	v_ashrrev_i32_e32 v28, 9, v28
	ds_read2_b32 v[12:13], v12 offset1:1
	ds_read2_b32 v[14:15], v14 offset1:1
	v_mul_hi_i32 v35, v30, s92
	v_mul_hi_i32 v36, v29, s92
	v_mul_hi_i32 v37, v32, s92
	v_mul_hi_i32 v38, v31, s92
	v_mul_hi_i32 v39, v26, s92
	v_mul_hi_i32 v40, v25, s92
	v_add_u32_e32 v27, v27, v33
	v_add_u32_e32 v28, v28, v34
	v_lshrrev_b32_e32 v33, 31, v35
	v_ashrrev_i32_e32 v34, 9, v35
	v_lshrrev_b32_e32 v35, 31, v36
	v_ashrrev_i32_e32 v36, 9, v36
	v_lshrrev_b32_e32 v41, 31, v37
	v_ashrrev_i32_e32 v37, 9, v37
	v_lshrrev_b32_e32 v42, 31, v38
	v_ashrrev_i32_e32 v38, 9, v38
	v_lshrrev_b32_e32 v43, 31, v39
	v_ashrrev_i32_e32 v39, 9, v39
	v_lshrrev_b32_e32 v44, 31, v40
	v_ashrrev_i32_e32 v40, 9, v40
	v_mul_i32_i24_e32 v45, 0xb00, v27
	v_mul_i32_i24_e32 v46, 0xb00, v28
	v_add_u32_e32 v33, v34, v33
	v_add_u32_e32 v34, v36, v35
	ds_read2_b32 v[16:17], v16 offset1:1
	ds_read2_b32 v[18:19], v18 offset1:1
	ds_read2_b32 v[20:21], v20 offset1:1
	ds_read2_b32 v[22:23], v22 offset1:1
	v_add_u32_e32 v35, v37, v41
	v_add_u32_e32 v36, v38, v42
	v_add_u32_e32 v37, v39, v43
	v_add_u32_e32 v38, v40, v44
	v_sub_u32_e32 v39, v5, v46
	v_sub_u32_e32 v40, v24, v45
	v_mul_i32_i24_e32 v41, 0xb00, v33
	v_mul_i32_i24_e32 v42, 0xb00, v34
	v_mul_i32_i24_e32 v43, 0xb00, v35
	v_mul_i32_i24_e32 v44, 0xb00, v36
	v_mul_i32_i24_e32 v45, 0xb00, v37
	v_mul_i32_i24_e32 v46, 0xb00, v38
	s_waitcnt lgkmcnt(6)
	v_and_b32_sdwa v47, v10, v153 dst_sel:DWORD dst_unused:UNUSED_PAD src0_sel:WORD_1 src1_sel:DWORD
	v_and_b32_sdwa v48, v8, v153 dst_sel:DWORD dst_unused:UNUSED_PAD src0_sel:WORD_1 src1_sel:DWORD
	v_and_b32_sdwa v49, v11, v153 dst_sel:DWORD dst_unused:UNUSED_PAD src0_sel:WORD_1 src1_sel:DWORD
	v_and_b32_sdwa v50, v9, v153 dst_sel:DWORD dst_unused:UNUSED_PAD src0_sel:WORD_1 src1_sel:DWORD
	v_lshlrev_b32_e32 v51, 1, v39
	v_lshlrev_b32_e32 v52, 1, v40
	v_sub_u32_e32 v42, v29, v42
	v_sub_u32_e32 v41, v30, v41
	v_sub_u32_e32 v44, v31, v44
	v_sub_u32_e32 v43, v32, v43
	v_sub_u32_e32 v46, v25, v46
	v_sub_u32_e32 v45, v26, v45
	v_add3_u32 v8, v8, v48, s91
	v_add3_u32 v10, v10, v47, s91
	v_add3_u32 v11, v11, v49, s91
	v_add3_u32 v9, v9, v50, s91
	v_and_b32_e32 v47, 0xffffff00, v51
	v_and_b32_e32 v48, 0xffffff00, v52
	s_waitcnt lgkmcnt(4)
	v_and_b32_sdwa v51, v15, v153 dst_sel:DWORD dst_unused:UNUSED_PAD src0_sel:WORD_1 src1_sel:DWORD
	v_and_b32_sdwa v52, v13, v153 dst_sel:DWORD dst_unused:UNUSED_PAD src0_sel:WORD_1 src1_sel:DWORD
	v_lshlrev_b32_e32 v53, 1, v42
	v_lshlrev_b32_e32 v54, 1, v41
	v_and_b32_e32 v39, 0x7f, v39
	v_and_b32_e32 v40, 0x7f, v40
	v_and_b32_sdwa v49, v14, v153 dst_sel:DWORD dst_unused:UNUSED_PAD src0_sel:WORD_1 src1_sel:DWORD
	v_and_b32_sdwa v50, v12, v153 dst_sel:DWORD dst_unused:UNUSED_PAD src0_sel:WORD_1 src1_sel:DWORD
	s_waitcnt lgkmcnt(3)
	v_and_b32_sdwa v58, v17, v153 dst_sel:DWORD dst_unused:UNUSED_PAD src0_sel:WORD_1 src1_sel:DWORD
	v_lshlrev_b32_e32 v59, 1, v44
	v_lshlrev_b32_e32 v60, 1, v43
	v_lshlrev_b32_e32 v65, 1, v46
	v_lshlrev_b32_e32 v66, 1, v45
	v_and_b32_e32 v11, 0xffff0000, v11
	v_and_b32_e32 v9, 0xffff0000, v9
	v_lshl_add_u32 v28, v28, 7, v47
	v_lshl_add_u32 v27, v27, 7, v48
	v_add3_u32 v15, v15, v51, s91
	v_add3_u32 v13, v13, v52, s91
	v_and_b32_e32 v47, 0xffffff00, v53
	v_and_b32_e32 v48, 0xffffff00, v54
	v_and_b32_e32 v42, 0x7f, v42
	v_and_b32_e32 v41, 0x7f, v41
	v_and_b32_sdwa v56, v16, v153 dst_sel:DWORD dst_unused:UNUSED_PAD src0_sel:WORD_1 src1_sel:DWORD
	s_waitcnt lgkmcnt(2)
	v_and_b32_sdwa v57, v19, v153 dst_sel:DWORD dst_unused:UNUSED_PAD src0_sel:WORD_1 src1_sel:DWORD
	s_waitcnt lgkmcnt(1)
	v_and_b32_sdwa v64, v21, v153 dst_sel:DWORD dst_unused:UNUSED_PAD src0_sel:WORD_1 src1_sel:DWORD
	v_add3_u32 v12, v12, v50, s91
	v_add3_u32 v14, v14, v49, s91
	v_add3_u32 v17, v17, v58, s91
	v_and_b32_e32 v49, 0xffffff00, v59
	v_and_b32_e32 v50, 0xffffff00, v60
	v_and_b32_e32 v51, 0xffffff00, v65
	v_and_b32_e32 v52, 0xffffff00, v66
	v_or_b32_sdwa v53, v11, v10 dst_sel:DWORD dst_unused:UNUSED_PAD src0_sel:DWORD src1_sel:WORD_1
	v_or_b32_sdwa v54, v9, v8 dst_sel:DWORD dst_unused:UNUSED_PAD src0_sel:DWORD src1_sel:WORD_1
	v_or_b32_e32 v8, v28, v39
	v_or_b32_e32 v9, v27, v40
	v_and_b32_e32 v10, 0xffff0000, v15
	v_and_b32_e32 v11, 0xffff0000, v13
	v_lshl_add_u32 v13, v34, 7, v47
	v_lshl_add_u32 v15, v33, 7, v48
	v_and_b32_sdwa v55, v18, v153 dst_sel:DWORD dst_unused:UNUSED_PAD src0_sel:WORD_1 src1_sel:DWORD
	v_and_b32_e32 v44, 0x7f, v44
	v_and_b32_e32 v43, 0x7f, v43
	v_and_b32_sdwa v62, v20, v153 dst_sel:DWORD dst_unused:UNUSED_PAD src0_sel:WORD_1 src1_sel:DWORD
	s_waitcnt lgkmcnt(0)
	v_and_b32_sdwa v63, v23, v153 dst_sel:DWORD dst_unused:UNUSED_PAD src0_sel:WORD_1 src1_sel:DWORD
	v_and_b32_e32 v46, 0x7f, v46
	v_and_b32_e32 v45, 0x7f, v45
	v_add3_u32 v16, v16, v56, s91
	v_add3_u32 v19, v19, v57, s91
	v_add3_u32 v21, v21, v64, s91
	v_and_b32_e32 v17, 0xffff0000, v17
	v_lshl_add_u32 v27, v36, 7, v49
	v_lshl_add_u32 v28, v35, 7, v50
	v_lshl_add_u32 v33, v38, 7, v51
	v_lshl_add_u32 v34, v37, 7, v52
	v_cndmask_b32_e32 v5, v8, v5, vcc
	v_cndmask_b32_e32 v24, v9, v24, vcc
	v_or_b32_sdwa v39, v11, v12 dst_sel:DWORD dst_unused:UNUSED_PAD src0_sel:DWORD src1_sel:WORD_1
	v_or_b32_e32 v12, v13, v42
	v_or_b32_e32 v13, v15, v41
	v_and_b32_sdwa v61, v22, v153 dst_sel:DWORD dst_unused:UNUSED_PAD src0_sel:WORD_1 src1_sel:DWORD
	v_add3_u32 v18, v18, v55, s91
	v_add3_u32 v20, v20, v62, s91
	v_add3_u32 v23, v23, v63, s91
	v_and_b32_e32 v19, 0xffff0000, v19
	v_and_b32_e32 v21, 0xffff0000, v21
	v_or_b32_sdwa v37, v10, v14 dst_sel:DWORD dst_unused:UNUSED_PAD src0_sel:DWORD src1_sel:WORD_1
	v_or_b32_sdwa v41, v17, v16 dst_sel:DWORD dst_unused:UNUSED_PAD src0_sel:DWORD src1_sel:WORD_1
	v_or_b32_e32 v14, v27, v44
	v_or_b32_e32 v15, v28, v43
	v_or_b32_e32 v16, v33, v46
	v_or_b32_e32 v17, v34, v45
	v_mad_u64_u32 v[8:9], s[58:59], v4, v5, 0
	v_mad_u64_u32 v[10:11], s[58:59], v2, v24, 0
	v_cndmask_b32_e32 v13, v13, v30, vcc
	v_add3_u32 v22, v22, v61, s91
	v_and_b32_e32 v23, 0xffff0000, v23
	v_or_b32_sdwa v40, v19, v18 dst_sel:DWORD dst_unused:UNUSED_PAD src0_sel:DWORD src1_sel:WORD_1
	v_or_b32_sdwa v43, v21, v20 dst_sel:DWORD dst_unused:UNUSED_PAD src0_sel:DWORD src1_sel:WORD_1
	v_ashrrev_i32_e32 v28, 31, v24
	v_ashrrev_i32_e32 v33, 31, v5
	v_cndmask_b32_e32 v5, v12, v29, vcc
	v_cndmask_b32_e32 v20, v14, v31, vcc
	v_cndmask_b32_e32 v15, v15, v32, vcc
	v_cndmask_b32_e32 v24, v16, v25, vcc
	v_cndmask_b32_e32 v26, v17, v26, vcc
	v_mov_b32_e32 v12, v9
	v_mov_b32_e32 v14, v11
	v_mad_u64_u32 v[18:19], s[58:59], v2, v13, 0
	v_or_b32_sdwa v42, v23, v22 dst_sel:DWORD dst_unused:UNUSED_PAD src0_sel:DWORD src1_sel:WORD_1
	v_ashrrev_i32_e32 v29, 31, v13
	v_ashrrev_i32_e32 v31, 31, v5
	v_mad_u64_u32 v[16:17], s[58:59], v4, v5, 0
	v_ashrrev_i32_e32 v5, 31, v15
	v_ashrrev_i32_e32 v35, 31, v20
	v_mad_u64_u32 v[20:21], s[58:59], v4, v20, 0
	v_mad_u64_u32 v[22:23], s[58:59], v2, v15, 0
	v_ashrrev_i32_e32 v44, 31, v26
	v_ashrrev_i32_e32 v45, 31, v24
	v_mad_u64_u32 v[24:25], s[58:59], v4, v24, 0
	v_mad_u64_u32 v[26:27], s[58:59], v2, v26, 0
	v_mad_u64_u32 v[12:13], s[58:59], v4, v33, v[12:13]
	v_mad_u64_u32 v[14:15], s[58:59], v2, v28, v[14:15]
	v_mov_b32_e32 v30, v19
	v_mov_b32_e32 v28, v17
	v_mov_b32_e32 v32, v21
	v_mov_b32_e32 v34, v23
	v_mov_b32_e32 v36, v25
	v_mov_b32_e32 v38, v27
	v_mov_b32_e32 v9, v12
	v_mov_b32_e32 v11, v14
	v_mad_u64_u32 v[14:15], s[58:59], v2, v29, v[30:31]
	s_add_i32 s5, s5, 8
	s_add_i32 s4, s4, 8
	s_add_i32 s56, s56, -8
	v_mad_u64_u32 v[12:13], s[58:59], v4, v31, v[28:29]
	v_mad_u64_u32 v[28:29], s[58:59], v4, v35, v[32:33]
	v_mad_u64_u32 v[30:31], s[58:59], v2, v5, v[34:35]
	v_mad_u64_u32 v[32:33], s[58:59], v4, v45, v[36:37]
	v_mad_u64_u32 v[34:35], s[58:59], v2, v44, v[38:39]
	v_lshl_add_u64 v[10:11], v[10:11], 1, v[6:7]
	v_lshl_add_u64 v[8:9], v[8:9], 1, v[6:7]
	v_mov_b32_e32 v19, v14
	s_cmp_lg_u32 s56, 0
	v_mov_b32_e32 v17, v12
	v_mov_b32_e32 v21, v28
	v_mov_b32_e32 v23, v30
	v_mov_b32_e32 v25, v32
	v_mov_b32_e32 v27, v34
	global_store_dword v[10:11], v54, off
	global_store_dword v[8:9], v53, off
	v_lshl_add_u64 v[8:9], v[18:19], 1, v[6:7]
	v_lshl_add_u64 v[10:11], v[16:17], 1, v[6:7]
	v_lshl_add_u64 v[12:13], v[22:23], 1, v[6:7]
	v_lshl_add_u64 v[14:15], v[20:21], 1, v[6:7]
	v_lshl_add_u64 v[16:17], v[26:27], 1, v[6:7]
	v_lshl_add_u64 v[18:19], v[24:25], 1, v[6:7]
	global_store_dword v[8:9], v39, off
	global_store_dword v[10:11], v37, off
	global_store_dword v[12:13], v41, off
	global_store_dword v[14:15], v40, off
	global_store_dword v[16:17], v43, off
	global_store_dword v[18:19], v42, off
	s_cbranch_scc1 .LBB0_110
	s_waitcnt vmcnt(47)
	v_mov_b64_e32 v[4:5], v[72:73]
	s_waitcnt vmcnt(46)
	v_mov_b64_e32 v[8:9], v[68:69]
	s_waitcnt vmcnt(45)
	v_mov_b64_e32 v[12:13], v[80:81]
	s_waitcnt vmcnt(44)
	v_mov_b64_e32 v[16:17], v[76:77]
	s_waitcnt vmcnt(43)
	v_mov_b64_e32 v[20:21], v[88:89]
	s_waitcnt vmcnt(42)
	v_mov_b64_e32 v[24:25], v[84:85]
	s_waitcnt vmcnt(41)
	v_mov_b64_e32 v[28:29], v[96:97]
	s_waitcnt vmcnt(40)
	v_mov_b64_e32 v[32:33], v[92:93]
	s_waitcnt vmcnt(39)
	v_mov_b64_e32 v[36:37], v[104:105]
	s_waitcnt vmcnt(38)
	v_mov_b64_e32 v[40:41], v[100:101]
	s_waitcnt vmcnt(37)
	v_mov_b64_e32 v[44:45], v[112:113]
	s_waitcnt vmcnt(36)
	v_mov_b64_e32 v[48:49], v[108:109]
	s_waitcnt vmcnt(35)
	v_mov_b64_e32 v[52:53], v[120:121]
	s_waitcnt vmcnt(34)
	v_mov_b64_e32 v[56:57], v[116:117]
	s_waitcnt vmcnt(33)
	v_mov_b64_e32 v[60:61], v[128:129]
	s_waitcnt vmcnt(32)
	v_mov_b64_e32 v[64:65], v[124:125]
	v_mov_b64_e32 v[6:7], v[74:75]
	v_mov_b64_e32 v[10:11], v[70:71]
	v_mov_b64_e32 v[14:15], v[82:83]
	v_mov_b64_e32 v[18:19], v[78:79]
	v_mov_b64_e32 v[22:23], v[90:91]
	v_mov_b64_e32 v[26:27], v[86:87]
	v_mov_b64_e32 v[30:31], v[98:99]
	v_mov_b64_e32 v[34:35], v[94:95]
	v_mov_b64_e32 v[38:39], v[106:107]
	v_mov_b64_e32 v[42:43], v[102:103]
	v_mov_b64_e32 v[46:47], v[114:115]
	v_mov_b64_e32 v[50:51], v[110:111]
	v_mov_b64_e32 v[54:55], v[122:123]
	v_mov_b64_e32 v[58:59], v[118:119]
	v_mov_b64_e32 v[62:63], v[130:131]
	v_mov_b64_e32 v[66:67], v[126:127]
	v_mov_b64_e32 v[134:135], v[146:147]
	v_mov_b32_e32 v2, v154
	v_mov_b32_e32 v3, v155
	v_mov_b32_e32 v144, v156
	v_mov_b32_e32 v132, v148
	s_andn2_b64 exec, exec, s[54:55]
	s_cbranch_execnz .LBB0_57
